# attention stages: K/V prefetch of the first two stage copies issued behind the stage's bias use instead of in front of the bias loads
# baseline (speedup 1.0000x reference)
.LBB0_1907:
	s_add_i32 s52, s53, 3
	s_cmp_gt_u32 s53, 8
	s_cselect_b64 s[44:45], -1, 0
.LBB0_1913:
	s_cmp_lt_u32 s53, 8
	s_cselect_b64 s[18:19], -1, 0
	s_cmp_gt_u32 s53, 7
	s_mov_b64 s[46:47], -1
	s_cbranch_scc0 .LBB0_1915
	s_and_b32 s46, s50, 0x4000
	v_add_u32_e32 v92, s46, v179
	v_add_u32_e32 v101, v92, v187
	v_add_u32_e32 v80, v101, v188
	ds_read_b128 v[72:75], v80
	v_add_u32_e32 v84, v92, v190
	v_add_u32_e32 v76, v84, v191
	v_add_u32_e32 v93, v101, v189
	v_add_u32_e32 v84, v84, v192
	ds_read_b128 v[76:79], v76
	ds_read_b128 v[80:83], v80 offset:4096
	ds_read_b128 v[84:87], v84
	ds_read_b128 v[88:91], v93
	s_waitcnt lgkmcnt(3)
	v_mfma_f32_16x16x32_bf16 v[76:79], v[76:79], v[0:3], 0
	v_add_u32_e32 v102, v92, v193
	v_add_u32_e32 v103, v102, v194
	ds_read_b128 v[92:95], v93 offset:4096
	v_mfma_f32_16x16x32_bf16 v[72:75], v[72:75], v[0:3], 0
	v_add_u32_e32 v223, v102, v195
	s_mov_b64 s[46:47], 0
	s_waitcnt lgkmcnt(1)
	v_mfma_f32_16x16x32_bf16 v[72:75], v[88:91], v[4:7], v[72:75]
	ds_read_b128 v[88:91], v103 offset:8192
	ds_read_b128 v[96:99], v103 offset:10240
	v_mfma_f32_16x16x32_bf16 v[76:79], v[84:87], v[4:7], v[76:79]
	s_nop 4
	v_mul_f32_e32 v84, 0x3e38aa3b, v72
	v_mul_f32_e32 v86, 0x3e38aa3b, v73
	v_mul_f32_e32 v104, 0x3e38aa3b, v74
	v_mul_f32_e32 v202, 0x3e38aa3b, v75
	v_max_f32_e32 v84, v84, v86
	v_mul_f32_e32 v85, 0x3e38aa3b, v76
	v_mul_f32_e32 v87, 0x3e38aa3b, v77
	v_max3_f32 v84, v84, v104, v202
	v_mul_f32_e32 v178, 0x3e38aa3b, v78
	v_mul_f32_e32 v203, 0x3e38aa3b, v79
	v_max3_f32 v84, v84, v85, v87
	v_max3_f32 v84, v84, v178, v203
	v_mov_b32_e32 v85, v84
	s_nop 1
	v_permlane16_swap_b32_e32 v84, v85
	v_max_f32_e32 v85, v85, v85
	v_max_f32_e32 v84, v84, v84
	v_max_f32_e32 v84, v84, v85
	v_mov_b32_e32 v85, v84
	s_nop 1
	v_permlane32_swap_b32_e32 v84, v85
	v_max3_f32 v178, v201, v84, v85
	v_fma_f32 v72, v72, s38, -v178
	v_exp_f32_e32 v206, v72
	v_fma_f32 v72, v73, s38, -v178
	v_exp_f32_e32 v207, v72
	v_fma_f32 v72, v74, s38, -v178
	v_exp_f32_e32 v208, v72
	v_fma_f32 v72, v75, s38, -v178
	v_exp_f32_e32 v209, v72
	v_fma_f32 v72, v76, s38, -v178
	v_exp_f32_e32 v210, v72
	v_fma_f32 v72, v77, s38, -v178
	v_exp_f32_e32 v211, v72
	v_fma_f32 v72, v78, s38, -v178
	v_sub_f32_e32 v84, v201, v178
	v_exp_f32_e32 v212, v72
	v_fma_f32 v72, v79, s38, -v178
	v_exp_f32_e32 v213, v72
	v_exp_f32_e32 v104, v84
	v_cvt_pk_bf16_f32 v72, v206, v207
	v_cvt_pk_bf16_f32 v73, v208, v209
	v_cvt_pk_bf16_f32 v74, v210, v211
	v_cvt_pk_bf16_f32 v75, v212, v213
	v_pk_mul_f32 v[76:77], v[64:65], v[104:105] op_sel_hi:[1,0]
	v_pk_mul_f32 v[78:79], v[66:67], v[104:105] op_sel_hi:[1,0]
	ds_read_b128 v[84:87], v103 offset:12288
	v_pk_mul_f32 v[202:203], v[56:57], v[104:105] op_sel_hi:[1,0]
	s_waitcnt lgkmcnt(2)
	v_mfma_f32_16x16x32_bf16 v[76:79], v[88:91], v[72:75], v[76:79]
	v_mul_f32_e64 v88, v60, v104
	v_mul_f32_e64 v89, v61, v104
	v_pk_mul_f32 v[90:91], v[62:63], v[104:105] op_sel_hi:[1,0]
	v_pk_mul_f32 v[204:205], v[58:59], v[104:105] op_sel_hi:[1,0]
	v_mfma_f32_16x16x32_bf16 v[80:83], v[80:83], v[0:3], 0
	s_waitcnt lgkmcnt(1)
	v_mfma_f32_16x16x32_bf16 v[88:91], v[96:99], v[72:75], v[88:91]
	ds_read_b128 v[96:99], v103 offset:14336
	v_add_f32_e32 v103, 0, v206
	v_add_f32_e32 v103, v207, v103
	s_waitcnt lgkmcnt(1)
	v_mfma_f32_16x16x32_bf16 v[84:87], v[84:87], v[72:75], v[202:205]
	v_add_f32_e32 v103, v208, v103
	v_add_f32_e32 v103, v209, v103
	v_add_f32_e32 v103, v210, v103
	v_pk_mul_f32 v[202:203], v[68:69], v[104:105] op_sel_hi:[1,0]
	v_pk_mul_f32 v[204:205], v[70:71], v[104:105] op_sel_hi:[1,0]
	v_mfma_f32_16x16x32_bf16 v[80:83], v[92:95], v[4:7], v[80:83]
	v_add_f32_e32 v103, v211, v103
	s_waitcnt lgkmcnt(0)
	v_mfma_f32_16x16x32_bf16 v[96:99], v[96:99], v[72:75], v[202:205]
	v_add_u32_e32 v72, v101, v191
	ds_read_b128 v[72:75], v72 offset:4608
	v_add_u32_e32 v101, v101, v192
	ds_read_b128 v[202:205], v101 offset:4608
	s_waitcnt lgkmcnt(1)
	v_mfma_f32_16x16x32_bf16 v[72:75], v[72:75], v[0:3], 0
	v_add_f32_e32 v101, v212, v103
	v_mul_f32_e32 v92, 0x3e38aa3b, v80
	v_mul_f32_e32 v94, 0x3e38aa3b, v81
	s_waitcnt lgkmcnt(0)
	v_mfma_f32_16x16x32_bf16 v[72:75], v[202:205], v[4:7], v[72:75]
	v_add_f32_e32 v222, v213, v101
	v_mul_f32_e32 v101, 0x3e38aa3b, v82
	v_mul_f32_e32 v103, 0x3e38aa3b, v83
	v_max_f32_e32 v92, v92, v94
	v_max3_f32 v92, v92, v101, v103
	s_nop 2
	v_mul_f32_e32 v93, 0x3e38aa3b, v72
	v_mul_f32_e32 v95, 0x3e38aa3b, v73
	v_mul_f32_e32 v102, 0x3e38aa3b, v74
	v_mul_f32_e32 v202, 0x3e38aa3b, v75
	v_max3_f32 v92, v92, v93, v95
	v_max3_f32 v92, v92, v102, v202
	v_mov_b32_e32 v93, v92
	s_nop 1
	v_permlane16_swap_b32_e32 v92, v93
	v_max_f32_e32 v93, v93, v93
	v_max_f32_e32 v92, v92, v92
	v_max_f32_e32 v92, v92, v93
	v_mov_b32_e32 v93, v92
	s_nop 1
	v_permlane32_swap_b32_e32 v92, v93
	v_max3_f32 v202, v178, v92, v93
	v_sub_f32_e32 v178, v178, v202
	v_fma_f32 v72, v72, s38, -v202
	v_exp_f32_e32 v178, v178
	v_exp_f32_e32 v101, v72
	v_fma_f32 v72, v73, s38, -v202
	v_exp_f32_e32 v102, v72
	v_fma_f32 v72, v74, s38, -v202
	v_exp_f32_e32 v103, v72
	v_fma_f32 v72, v75, s38, -v202
	ds_read_b128 v[206:209], v223 offset:8192
	ds_read_b128 v[210:213], v223 offset:10240
	ds_read_b128 v[214:217], v223 offset:12288
	v_fma_f32 v80, v80, s38, -v202
	v_exp_f32_e32 v203, v72
	v_pk_mul_f32 v[74:75], v[78:79], v[178:179] op_sel_hi:[1,0]
	v_pk_mul_f32 v[72:73], v[76:77], v[178:179] op_sel_hi:[1,0]
	ds_read_b128 v[76:79], v223 offset:14336
	v_exp_f32_e32 v92, v80
	v_fma_f32 v80, v81, s38, -v202
	v_exp_f32_e32 v93, v80
	v_fma_f32 v80, v82, s38, -v202
	v_exp_f32_e32 v94, v80
	v_fma_f32 v80, v83, s38, -v202
	v_exp_f32_e32 v95, v80
	v_cvt_pk_bf16_f32 v218, v92, v93
	v_cvt_pk_bf16_f32 v220, v101, v102
	v_cvt_pk_bf16_f32 v221, v103, v203
	v_cvt_pk_bf16_f32 v219, v94, v95
	v_pk_mul_f32 v[82:83], v[90:91], v[178:179] op_sel_hi:[1,0]
	v_pk_mul_f32 v[80:81], v[88:89], v[178:179] op_sel_hi:[1,0]
	v_fmac_f32_e32 v222, v100, v104
	v_pk_mul_f32 v[86:87], v[86:87], v[178:179] op_sel_hi:[1,0]
	v_pk_mul_f32 v[84:85], v[84:85], v[178:179] op_sel_hi:[1,0]
	v_pk_mul_f32 v[98:99], v[98:99], v[178:179] op_sel_hi:[1,0]
	v_pk_mul_f32 v[96:97], v[96:97], v[178:179] op_sel_hi:[1,0]
	s_waitcnt lgkmcnt(3)
	v_mfma_f32_16x16x32_bf16 v[72:75], v[206:209], v[218:221], v[72:75]
	s_waitcnt lgkmcnt(2)
	v_mfma_f32_16x16x32_bf16 v[80:83], v[210:213], v[218:221], v[80:83]
	s_waitcnt lgkmcnt(1)
	v_mfma_f32_16x16x32_bf16 v[88:91], v[214:217], v[218:221], v[84:87]
	s_nop 2
	v_mul_f32_e32 v84, v222, v178
	s_waitcnt lgkmcnt(0)
	v_mfma_f32_16x16x32_bf16 v[96:99], v[76:79], v[218:221], v[96:99]

.LBB0_1918:
	s_or_b64 exec, exec, s[46:47]
	s_nop 4
	v_mul_f32_e32 v88, 0x3e38aa3b, v92
	v_mul_f32_e32 v89, 0x3e38aa3b, v89
	v_mul_f32_e32 v92, 0x3e38aa3b, v93
	v_mul_f32_e32 v90, 0x3e38aa3b, v90
	v_mul_f32_e32 v91, 0x3e38aa3b, v91
	s_waitcnt vmcnt(6)
	v_fmac_f32_e32 v89, 0x3fb8aa3b, v99
	s_waitcnt vmcnt(2)
	v_fmac_f32_e32 v92, 0x3fb8aa3b, v101
	v_cndmask_b32_e64 v89, v176, v89, s[4:5]
	v_fmac_f32_e32 v90, 0x3fb8aa3b, v98
	v_fmac_f32_e32 v91, 0x3fb8aa3b, v97
	v_fmac_f32_e32 v88, 0x3fb8aa3b, v96
	v_cndmask_b32_e64 v96, v176, v92, s[12:13]
	v_max_f32_e32 v92, v103, v103
	v_mul_f32_e32 v93, 0x3e38aa3b, v94
	v_mul_f32_e32 v94, 0x3e38aa3b, v95
	v_cndmask_b32_e64 v90, v176, v90, s[6:7]
	v_cndmask_b32_e64 v91, v176, v91, s[8:9]
	v_max_f32_e32 v92, v92, v89
	v_cndmask_b32_e64 v88, v176, v88, s[10:11]
	s_waitcnt vmcnt(1)
	v_fmac_f32_e32 v93, 0x3fb8aa3b, v102
	s_waitcnt vmcnt(0)
	v_fmac_f32_e32 v94, 0x3fb8aa3b, v104
	v_mov_b32_e32 v227, 0
	s_and_b64 vcc, exec, s[44:45]
	s_cbranch_vccnz .Lat_pf0_done
	s_cmp_gt_u32 s53, 4
	s_mov_b64 s[100:101], -1
	s_cbranch_scc0 .LBB0_1910
	v_add_u32_e32 v226, s51, v180
	v_lshlrev_b64 v[8:9], 10, v[226:227]
	v_lshl_add_u64 v[12:13], v[114:115], 0, v[8:9]
	s_mov_b64 s[100:101], 0
.LBB0_1910:
	s_andn2_b64 vcc, exec, s[100:101]
	v_mov_b32_e32 v8, s51
	v_mov_b64_e32 v[10:11], v[110:111]
	s_cbranch_vccnz .LBB0_1912
	v_add_lshl_u32 v8, s52, v181, 6
	v_lshl_add_u64 v[12:13], v[138:139], 0, v[174:175]
	v_mov_b64_e32 v[10:11], v[108:109]
.LBB0_1912:
	v_lshlrev_b32_e32 v226, 1, v112
	v_lshl_add_u64 v[10:11], v[10:11], 0, v[226:227]
	v_mov_b32_e32 v9, v227
	v_lshl_add_u64 v[20:21], v[8:9], 1, v[10:11]
	global_load_dwordx4 v[8:11], v[12:13], off offset:16
	s_nop 0
	global_load_dwordx4 v[12:15], v[12:13], off
	s_nop 0
	global_load_dwordx4 v[16:19], v[20:21], off offset:16
	s_nop 0
	global_load_dwordx4 v[20:23], v[20:21], off
.Lat_pf0_done:
	v_max3_f32 v92, v92, v90, v91
	v_cndmask_b32_e64 v97, v176, v93, s[14:15]
	v_cndmask_b32_e64 v98, v176, v94, s[16:17]
	v_max3_f32 v92, v92, v88, v96
	v_max3_f32 v92, v92, v97, v98
	v_mov_b32_e32 v93, v92
	s_nop 1
	v_permlane16_swap_b32_e32 v92, v93
	v_max_f32_e32 v93, v93, v93
	v_max_f32_e32 v92, v92, v92
	v_max_f32_e32 v92, v92, v93
	v_mov_b32_e32 v93, v92
	s_nop 1
	v_permlane32_swap_b32_e32 v92, v93
	v_max3_f32 v202, v201, v92, v93
	v_sub_f32_e32 v88, v88, v202
	v_sub_f32_e32 v89, v89, v202
	v_exp_f32_e32 v101, v88
	v_sub_f32_e32 v88, v96, v202
	v_exp_f32_e32 v93, v89
	v_sub_f32_e32 v89, v90, v202
	v_exp_f32_e32 v102, v88
	v_sub_f32_e32 v88, v97, v202
	v_sub_f32_e32 v99, v201, v202
	v_sub_f32_e32 v92, v103, v202
	v_exp_f32_e32 v94, v89
	v_sub_f32_e32 v89, v91, v202
	v_exp_f32_e32 v103, v88
	v_sub_f32_e32 v88, v98, v202
	v_exp_f32_e32 v92, v92
	v_exp_f32_e32 v95, v89
	v_exp_f32_e32 v203, v88
	v_exp_f32_e32 v104, v99
	v_cvt_pk_bf16_f32 v96, v92, v93
	v_cvt_pk_bf16_f32 v97, v94, v95
	v_cvt_pk_bf16_f32 v98, v101, v102
	v_cvt_pk_bf16_f32 v99, v103, v203
	v_pk_mul_f32 v[56:57], v[56:57], v[104:105] op_sel_hi:[1,0]
	v_pk_mul_f32 v[58:59], v[58:59], v[104:105] op_sel_hi:[1,0]
	v_pk_mul_f32 v[64:65], v[64:65], v[104:105] op_sel_hi:[1,0]
	v_pk_mul_f32 v[66:67], v[66:67], v[104:105] op_sel_hi:[1,0]
	v_pk_mul_f32 v[60:61], v[60:61], v[104:105] op_sel_hi:[1,0]
	v_pk_mul_f32 v[62:63], v[62:63], v[104:105] op_sel_hi:[1,0]
	s_waitcnt lgkmcnt(1)
	v_mfma_f32_16x16x32_bf16 v[88:91], v[84:87], v[96:99], v[56:59]
	v_mul_f32_e32 v84, v100, v104
	s_nop 1
	v_pk_mul_f32 v[56:57], v[68:69], v[104:105] op_sel_hi:[1,0]
	v_pk_mul_f32 v[58:59], v[70:71], v[104:105] op_sel_hi:[1,0]
	v_mfma_f32_16x16x32_bf16 v[72:75], v[72:75], v[96:99], v[64:67]
	v_mfma_f32_16x16x32_bf16 v[80:83], v[80:83], v[96:99], v[60:63]
	s_waitcnt lgkmcnt(0)
	v_mfma_f32_16x16x32_bf16 v[96:99], v[76:79], v[96:99], v[56:59]
.LBB0_1919:
	s_add_i32 s46, s50, 0x4000
	s_and_b32 s46, s46, 0x4000
	s_nop 0
	v_add_u32_e32 v56, s46, v179
	v_add_u32_e32 v57, v56, v182
	v_add_u32_e32 v58, v57, v185
	v_add_u32_e32 v57, v57, v186
	s_waitcnt vmcnt(6)
	ds_write_b128 v58, v[28:31]
	ds_write_b128 v57, v[24:27]
	s_waitcnt vmcnt(4)
	ds_write_b128 v58, v[36:39] offset:8192
	ds_write_b128 v57, v[32:35] offset:8192
	s_waitcnt lgkmcnt(0)
	s_barrier
.LBB0_1925:
	v_add_f32_e32 v57, 0, v92
	v_add_f32_e32 v57, v57, v93
	v_add_f32_e32 v57, v57, v94
	v_add_f32_e32 v57, v57, v95
	v_add_f32_e32 v57, v57, v101
	v_add_f32_e32 v57, v57, v102
	v_add_f32_e32 v57, v57, v103
	v_add_f32_e32 v57, v57, v203
	s_cmp_lt_u32 s53, 7
	v_add_f32_e32 v104, v84, v57
	s_cselect_b64 s[18:19], -1, 0
	s_cmp_gt_u32 s53, 6
	s_mov_b64 s[46:47], -1
	s_cbranch_scc0 .LBB0_1927
	v_add_u32_e32 v57, v56, v187
	v_add_u32_e32 v66, v57, v188
	ds_read_b128 v[58:61], v66
	v_add_u32_e32 v70, v56, v190
	v_add_u32_e32 v62, v70, v191
	v_add_u32_e32 v71, v57, v189
	v_add_u32_e32 v70, v70, v192
	ds_read_b128 v[62:65], v62
	ds_read_b128 v[66:69], v66 offset:4096
	ds_read_b128 v[76:79], v70
	ds_read_b128 v[84:87], v71
	s_waitcnt lgkmcnt(3)
	v_mfma_f32_16x16x32_bf16 v[62:65], v[62:65], v[0:3], 0
	v_add_u32_e32 v178, v56, v193
	ds_read_b128 v[92:95], v71 offset:4096
	v_add_u32_e32 v71, v178, v194
	v_mfma_f32_16x16x32_bf16 v[58:61], v[58:61], v[0:3], 0
	s_mov_b64 s[46:47], 0
	s_waitcnt lgkmcnt(1)
	v_mfma_f32_16x16x32_bf16 v[58:61], v[84:87], v[4:7], v[58:61]
	ds_read_b128 v[84:87], v71 offset:8192
	ds_read_b128 v[100:103], v71 offset:10240
	v_mfma_f32_16x16x32_bf16 v[62:65], v[76:79], v[4:7], v[62:65]
	s_nop 4
	v_mul_f32_e32 v70, 0x3e38aa3b, v58
	v_mul_f32_e32 v77, 0x3e38aa3b, v59
	v_mul_f32_e32 v79, 0x3e38aa3b, v60
	v_mul_f32_e32 v203, 0x3e38aa3b, v61
	v_max_f32_e32 v70, v70, v77
	v_mul_f32_e32 v76, 0x3e38aa3b, v62
	v_mul_f32_e32 v78, 0x3e38aa3b, v63
	v_max3_f32 v70, v70, v79, v203
	v_mul_f32_e32 v201, 0x3e38aa3b, v64
	v_mul_f32_e32 v204, 0x3e38aa3b, v65
	v_max3_f32 v70, v70, v76, v78
	v_max3_f32 v70, v70, v201, v204
	v_mov_b32_e32 v76, v70
	s_nop 1
	v_permlane16_swap_b32_e32 v70, v76
	v_max_f32_e32 v76, v76, v76
	v_max_f32_e32 v70, v70, v70
	v_max_f32_e32 v70, v70, v76
	v_mov_b32_e32 v76, v70
	s_nop 1
	v_permlane32_swap_b32_e32 v70, v76
	v_max3_f32 v201, v202, v70, v76
	v_fma_f32 v58, v58, s38, -v201
	v_exp_f32_e32 v203, v58
	v_fma_f32 v58, v59, s38, -v201
	v_exp_f32_e32 v208, v58
	v_fma_f32 v58, v60, s38, -v201
	v_exp_f32_e32 v209, v58
	v_fma_f32 v58, v61, s38, -v201
	v_exp_f32_e32 v210, v58
	v_fma_f32 v58, v62, s38, -v201
	v_exp_f32_e32 v211, v58
	v_fma_f32 v58, v63, s38, -v201
	v_exp_f32_e32 v216, v58
	v_fma_f32 v58, v64, s38, -v201
	v_sub_f32_e32 v70, v202, v201
	v_exp_f32_e32 v217, v58
	v_fma_f32 v58, v65, s38, -v201
	v_exp_f32_e32 v218, v58
	v_exp_f32_e32 v70, v70
	v_cvt_pk_bf16_f32 v58, v203, v208
	v_cvt_pk_bf16_f32 v59, v209, v210
	v_cvt_pk_bf16_f32 v60, v211, v216
	v_cvt_pk_bf16_f32 v61, v217, v218
	v_pk_mul_f32 v[62:63], v[72:73], v[70:71] op_sel_hi:[1,0]
	v_pk_mul_f32 v[64:65], v[74:75], v[70:71] op_sel_hi:[1,0]
	ds_read_b128 v[76:79], v71 offset:12288
	v_pk_mul_f32 v[204:205], v[88:89], v[70:71] op_sel_hi:[1,0]
	s_waitcnt lgkmcnt(2)
	v_mfma_f32_16x16x32_bf16 v[62:65], v[84:87], v[58:61], v[62:65]
	v_mul_f32_e64 v84, v80, v70
	v_mul_f32_e64 v85, v81, v70
	v_pk_mul_f32 v[86:87], v[82:83], v[70:71] op_sel_hi:[1,0]
	v_pk_mul_f32 v[206:207], v[90:91], v[70:71] op_sel_hi:[1,0]
	v_mfma_f32_16x16x32_bf16 v[66:69], v[66:69], v[0:3], 0
	s_waitcnt lgkmcnt(1)
	v_mfma_f32_16x16x32_bf16 v[84:87], v[100:103], v[58:61], v[84:87]
	ds_read_b128 v[100:103], v71 offset:14336
	s_waitcnt lgkmcnt(1)
	v_mfma_f32_16x16x32_bf16 v[212:215], v[76:79], v[58:61], v[204:207]
	v_mul_f32_e64 v78, v98, v70
	v_mul_f32_e64 v79, v99, v70
	v_pk_mul_f32 v[76:77], v[96:97], v[70:71] op_sel_hi:[1,0]
	v_add_f32_e32 v71, 0, v203
	v_add_f32_e32 v71, v208, v71
	s_waitcnt lgkmcnt(0)
	v_mfma_f32_16x16x32_bf16 v[100:103], v[100:103], v[58:61], v[76:79]
	v_add_u32_e32 v58, v57, v191
	ds_read_b128 v[58:61], v58 offset:4608
	v_add_u32_e32 v57, v57, v192
	ds_read_b128 v[76:79], v57 offset:4608
	s_waitcnt lgkmcnt(1)
	v_mfma_f32_16x16x32_bf16 v[58:61], v[58:61], v[0:3], 0
	v_add_f32_e32 v71, v209, v71
	v_add_f32_e32 v71, v210, v71
	v_add_f32_e32 v71, v211, v71
	v_mfma_f32_16x16x32_bf16 v[66:69], v[92:95], v[4:7], v[66:69]
	v_add_f32_e32 v71, v216, v71
	v_add_f32_e32 v57, v217, v71
	v_add_u32_e32 v71, v178, v195
	s_waitcnt lgkmcnt(0)
	v_mfma_f32_16x16x32_bf16 v[58:61], v[76:79], v[4:7], v[58:61]
	v_add_f32_e32 v57, v218, v57
	s_nop 1
	v_mul_f32_e32 v76, 0x3e38aa3b, v66
	v_mul_f32_e32 v78, 0x3e38aa3b, v67
	v_mul_f32_e32 v178, 0x3e38aa3b, v68
	v_mul_f32_e32 v204, 0x3e38aa3b, v69
	v_max_f32_e32 v76, v76, v78
	v_mul_f32_e32 v77, 0x3e38aa3b, v58
	v_mul_f32_e32 v79, 0x3e38aa3b, v59
	v_max3_f32 v76, v76, v178, v204
	v_mul_f32_e32 v203, 0x3e38aa3b, v60
	v_mul_f32_e32 v205, 0x3e38aa3b, v61
	v_max3_f32 v76, v76, v77, v79
	v_max3_f32 v76, v76, v203, v205
	v_mov_b32_e32 v77, v76
	s_nop 1
	v_permlane16_swap_b32_e32 v76, v77
	v_max_f32_e32 v77, v77, v77
	v_max_f32_e32 v76, v76, v76
	v_max_f32_e32 v76, v76, v77
	v_mov_b32_e32 v77, v76
	s_nop 1
	v_permlane32_swap_b32_e32 v76, v77
	v_max3_f32 v203, v201, v76, v77
	v_sub_f32_e32 v76, v201, v203
	v_fma_f32 v58, v58, s38, -v203
	v_exp_f32_e32 v178, v76
	v_exp_f32_e32 v207, v58
	v_fma_f32 v58, v59, s38, -v203
	v_fma_f32 v66, v66, s38, -v203
	v_exp_f32_e32 v208, v58
	v_fma_f32 v58, v60, s38, -v203
	v_exp_f32_e32 v201, v66
	v_fma_f32 v66, v67, s38, -v203
	v_exp_f32_e32 v209, v58
	v_fma_f32 v58, v61, s38, -v203
	ds_read_b128 v[92:95], v71 offset:8192
	ds_read_b128 v[216:219], v71 offset:10240
	ds_read_b128 v[220:223], v71 offset:12288
	v_exp_f32_e32 v204, v66
	v_fma_f32 v66, v68, s38, -v203
	v_exp_f32_e32 v210, v58
	v_pk_mul_f32 v[60:61], v[64:65], v[178:179] op_sel_hi:[1,0]
	v_pk_mul_f32 v[58:59], v[62:63], v[178:179] op_sel_hi:[1,0]
	ds_read_b128 v[62:65], v71 offset:14336
	v_exp_f32_e32 v205, v66
	v_fma_f32 v66, v69, s38, -v203
	v_exp_f32_e32 v206, v66
	v_cvt_pk_bf16_f32 v66, v201, v204
	v_cvt_pk_bf16_f32 v68, v207, v208
	v_cvt_pk_bf16_f32 v69, v209, v210
	v_cvt_pk_bf16_f32 v67, v205, v206
	v_fmac_f32_e32 v57, v104, v70
	v_pk_mul_f32 v[102:103], v[102:103], v[178:179] op_sel_hi:[1,0]
	s_waitcnt lgkmcnt(3)
	v_mfma_f32_16x16x32_bf16 v[76:79], v[92:95], v[66:69], v[58:61]
	v_mul_f32_e64 v100, v100, v178
	v_mul_f32_e64 v101, v101, v178
	s_nop 0
	v_pk_mul_f32 v[60:61], v[86:87], v[178:179] op_sel_hi:[1,0]
	v_pk_mul_f32 v[58:59], v[84:85], v[178:179] op_sel_hi:[1,0]
	s_waitcnt lgkmcnt(0)
	v_mfma_f32_16x16x32_bf16 v[100:103], v[62:65], v[66:69], v[100:103]
	v_mfma_f32_16x16x32_bf16 v[84:87], v[216:219], v[66:69], v[58:61]
	s_nop 2
	v_mul_f32_e64 v60, v214, v178
	v_mul_f32_e64 v61, v215, v178
	v_pk_mul_f32 v[58:59], v[212:213], v[178:179] op_sel_hi:[1,0]
	s_nop 1
	v_mfma_f32_16x16x32_bf16 v[92:95], v[220:223], v[66:69], v[58:61]
	s_nop 2
	v_mul_f32_e32 v60, v57, v178

.LBB0_1930:
	s_or_b64 exec, exec, s[46:47]
	v_mul_f32_e32 v77, 0x3e38aa3b, v77
	v_mul_f32_e32 v78, 0x3e38aa3b, v78
	v_mul_f32_e32 v79, 0x3e38aa3b, v79
	s_waitcnt vmcnt(6)
	v_fmac_f32_e32 v77, 0x3fb8aa3b, v95
	v_mul_f32_e32 v76, 0x3e38aa3b, v84
	v_mul_f32_e32 v84, 0x3e38aa3b, v85
	v_mul_f32_e32 v85, 0x3e38aa3b, v86
	v_mul_f32_e32 v86, 0x3e38aa3b, v87
	v_cndmask_b32_e64 v77, v176, v77, s[4:5]
	s_waitcnt vmcnt(5)
	v_fmac_f32_e32 v78, 0x3fb8aa3b, v94
	s_waitcnt vmcnt(4)
	v_fmac_f32_e32 v79, 0x3fb8aa3b, v93
	v_max_f32_e32 v87, v102, v102
	v_cndmask_b32_e64 v78, v176, v78, s[6:7]
	v_cndmask_b32_e64 v79, v176, v79, s[8:9]
	s_waitcnt vmcnt(3)
	v_fmac_f32_e32 v76, 0x3fb8aa3b, v92
	s_waitcnt vmcnt(2)
	v_fmac_f32_e32 v84, 0x3fb8aa3b, v100
	v_max_f32_e32 v87, v87, v77
	v_cndmask_b32_e64 v76, v176, v76, s[10:11]
	v_cndmask_b32_e64 v84, v176, v84, s[12:13]
	s_waitcnt vmcnt(1)
	v_fmac_f32_e32 v85, 0x3fb8aa3b, v101
	s_waitcnt vmcnt(0)
	v_fmac_f32_e32 v86, 0x3fb8aa3b, v103
	s_cmp_lt_u32 s53, 8
	s_cbranch_scc0 .Lat_pf1_done
	v_mov_b32_e32 v227, 0
	s_cmp_gt_u32 s53, 3
	s_mov_b64 s[100:101], -1
	s_cbranch_scc0 .LBB0_1922
	s_add_i32 s46, s51, 64
	v_add_u32_e32 v226, s46, v180
	v_lshlrev_b64 v[24:25], 10, v[226:227]
	v_lshl_add_u64 v[28:29], v[114:115], 0, v[24:25]
	s_mov_b64 s[100:101], 0
.LBB0_1922:
	s_andn2_b64 vcc, exec, s[100:101]
	v_mov_b32_e32 v24, s46
	v_mov_b64_e32 v[26:27], v[110:111]
	s_cbranch_vccnz .LBB0_1924
	v_add_lshl_u32 v24, v199, s53, 6
	v_lshl_add_u64 v[28:29], v[138:139], 0, v[140:141]
	v_mov_b64_e32 v[26:27], v[108:109]
.LBB0_1924:
	v_lshlrev_b32_e32 v226, 1, v112
	v_lshl_add_u64 v[26:27], v[26:27], 0, v[226:227]
	v_mov_b32_e32 v25, v227
	v_lshl_add_u64 v[36:37], v[24:25], 1, v[26:27]
	global_load_dwordx4 v[24:27], v[28:29], off offset:16
	s_nop 0
	global_load_dwordx4 v[28:31], v[28:29], off
	s_nop 0
	global_load_dwordx4 v[32:35], v[36:37], off offset:16
	s_nop 0
	global_load_dwordx4 v[36:39], v[36:37], off
.Lat_pf1_done:
	v_max3_f32 v87, v87, v78, v79
	v_cndmask_b32_e64 v85, v176, v85, s[14:15]
	v_cndmask_b32_e64 v86, v176, v86, s[16:17]
	v_max3_f32 v87, v87, v76, v84
	v_max3_f32 v87, v87, v85, v86
	v_mov_b32_e32 v92, v87
	s_nop 1
	v_permlane16_swap_b32_e32 v87, v92
	v_max_f32_e32 v92, v92, v92
	v_max_f32_e32 v87, v87, v87
	v_max_f32_e32 v87, v87, v92
	v_mov_b32_e32 v92, v87
	s_nop 1
	v_permlane32_swap_b32_e32 v87, v92
	v_max3_f32 v203, v202, v87, v92
	v_sub_f32_e32 v76, v76, v203
	v_sub_f32_e32 v77, v77, v203
	v_exp_f32_e32 v207, v76
	v_sub_f32_e32 v76, v84, v203
	v_exp_f32_e32 v204, v77
	v_sub_f32_e32 v77, v78, v203
	v_exp_f32_e32 v208, v76
	v_sub_f32_e32 v76, v85, v203
	v_sub_f32_e32 v87, v202, v203
	v_sub_f32_e32 v92, v102, v203
	v_exp_f32_e32 v205, v77
	v_sub_f32_e32 v77, v79, v203
	v_exp_f32_e32 v209, v76
	v_sub_f32_e32 v76, v86, v203
	v_exp_f32_e32 v201, v92
	v_exp_f32_e32 v206, v77
	v_exp_f32_e32 v210, v76
	v_exp_f32_e32 v178, v87
	v_cvt_pk_bf16_f32 v100, v201, v204
	v_cvt_pk_bf16_f32 v101, v205, v206
	v_cvt_pk_bf16_f32 v102, v207, v208
	v_cvt_pk_bf16_f32 v103, v209, v210
	v_pk_mul_f32 v[72:73], v[72:73], v[178:179] op_sel_hi:[1,0]
	v_pk_mul_f32 v[74:75], v[74:75], v[178:179] op_sel_hi:[1,0]
	s_waitcnt lgkmcnt(3)
	s_nop 0
	v_mfma_f32_16x16x32_bf16 v[76:79], v[68:71], v[100:103], v[72:75]
	v_mul_f32_e64 v68, v80, v178
	v_mul_f32_e64 v69, v81, v178
	v_pk_mul_f32 v[70:71], v[82:83], v[178:179] op_sel_hi:[1,0]
	s_waitcnt lgkmcnt(2)
	s_nop 0
	v_mfma_f32_16x16x32_bf16 v[84:87], v[64:67], v[100:103], v[68:71]
	v_mul_f32_e64 v64, v88, v178
	v_mul_f32_e64 v65, v89, v178
	v_pk_mul_f32 v[66:67], v[90:91], v[178:179] op_sel_hi:[1,0]
	s_waitcnt lgkmcnt(1)
	s_nop 0
	v_mfma_f32_16x16x32_bf16 v[92:95], v[60:63], v[100:103], v[64:67]
	v_mul_f32_e64 v62, v96, v178
	v_mul_f32_e64 v63, v97, v178
	v_mul_f32_e32 v60, v104, v178
	v_pk_mul_f32 v[64:65], v[98:99], v[178:179] op_sel_hi:[1,0]
	s_waitcnt lgkmcnt(0)
	s_nop 0
	v_mfma_f32_16x16x32_bf16 v[100:103], v[56:59], v[100:103], v[62:65]
